# v034 + GU epilogue reads the row sum-of-squares partials from an LDS staging area filled by LDS-DMA during the first K iteration (static LDS +16 KB)
# speedup vs baseline: 1.0115x; 1.0013x over previous
.LBB0_1436:
	s_add_u32 s28, s6, 0xfffc0080
	s_addc_u32 s29, s7, -1
	s_add_i32 s71, 0, 0x10000
	v_add_u32_e32 v140, s71, v200
	ds_read_b128 v[128:131], v140
	ds_read_b128 v[132:135], v140 offset:1024
	ds_read_b128 v[136:139], v140 offset:2048
	ds_read_b128 v[140:143], v140 offset:3072
	s_cmp_eq_u32 s70, 12
	s_cselect_b32 s53, s17, s29
	s_cselect_b32 s52, s66, s28
	s_cselect_b32 s51, s13, s69
	s_cselect_b32 s50, s67, s68
	v_lshl_add_u64 v[174:175], s[6:7], 0, v[162:163]
	s_add_i32 m0, s56, 0xc000
	ds_read_b128 v[144:147], v201
	ds_read_b128 v[152:155], v201 offset:2048
	ds_read_b128 v[170:173], v201 offset:4096
	ds_read_b128 v[192:195], v201 offset:6144
	ds_read_b128 v[148:151], v201 offset:1024
	ds_read_b128 v[166:169], v201 offset:3072
	ds_read_b128 v[188:191], v201 offset:5120
	ds_read_b128 v[202:205], v201 offset:7168
	global_load_lds_dwordx4 v[174:175], off
	v_lshl_add_u64 v[174:175], s[6:7], 0, v[164:165]
	s_add_i32 m0, s56, 0xe000
	s_nop 0
	global_load_lds_dwordx4 v[174:175], off
	s_waitcnt lgkmcnt(8)
	s_barrier
	s_waitcnt lgkmcnt(7)
	v_mfma_f32_16x16x32_bf16 v[124:127], v[128:131], v[144:147], v[124:127]
	v_mfma_f32_16x16x32_bf16 v[116:119], v[136:139], v[144:147], v[116:119]
	s_waitcnt lgkmcnt(6)
	v_mfma_f32_16x16x32_bf16 v[108:111], v[128:131], v[152:155], v[108:111]
	v_mfma_f32_16x16x32_bf16 v[100:103], v[136:139], v[152:155], v[100:103]
	s_waitcnt lgkmcnt(5)
	v_mfma_f32_16x16x32_bf16 v[92:95], v[128:131], v[170:173], v[92:95]
	v_mfma_f32_16x16x32_bf16 v[84:87], v[136:139], v[170:173], v[84:87]
	s_waitcnt lgkmcnt(4)
	v_mfma_f32_16x16x32_bf16 v[76:79], v[128:131], v[192:195], v[76:79]
	v_mfma_f32_16x16x32_bf16 v[68:71], v[136:139], v[192:195], v[68:71]
	s_waitcnt lgkmcnt(3)
	v_mfma_f32_16x16x32_bf16 v[124:127], v[132:135], v[148:151], v[124:127]
	v_mfma_f32_16x16x32_bf16 v[116:119], v[140:143], v[148:151], v[116:119]
	s_waitcnt lgkmcnt(2)
	v_mfma_f32_16x16x32_bf16 v[108:111], v[132:135], v[166:169], v[108:111]
	v_mfma_f32_16x16x32_bf16 v[100:103], v[140:143], v[166:169], v[100:103]
	s_waitcnt lgkmcnt(1)
	v_mfma_f32_16x16x32_bf16 v[92:95], v[132:135], v[188:191], v[92:95]
	v_mfma_f32_16x16x32_bf16 v[84:87], v[140:143], v[188:191], v[84:87]
	s_waitcnt lgkmcnt(0)
	v_mfma_f32_16x16x32_bf16 v[76:79], v[132:135], v[202:205], v[76:79]
	v_mfma_f32_16x16x32_bf16 v[68:71], v[140:143], v[202:205], v[68:71]
	s_barrier
	s_cmp_eq_u32 s70, -2
	s_cbranch_scc0 .Lrs_skip_gu
	s_lshl_b32 s98, s4, 14
	s_lshl_b32 s99, s24, 5
	s_add_i32 s98, s98, s99
	v_and_b32_e32 v240, 63, v231
	v_lshl_add_u32 v240, v240, 4, s98
	v_mov_b32_e32 v241, 0
	s_add_i32 m0, s99, 0x20010
	v_lshl_add_u64 v[240:241], s[8:9], 0, v[240:241]
	global_load_lds_dwordx4 v[240:241], off
	global_load_lds_dwordx4 v[240:241], off offset:1024
.Lrs_skip_gu:
	s_add_i32 s28, 0, 0x14000
	v_add_u32_e32 v174, s28, v200
	s_add_i32 s29, s71, s55
	ds_read_b128 v[206:209], v174
	ds_read_b128 v[210:213], v174 offset:1024
	ds_read_b128 v[214:217], v174 offset:2048
	ds_read_b128 v[232:235], v174 offset:3072
	v_lshl_add_u64 v[174:175], s[50:51], 0, v[176:177]
	s_mov_b32 m0, s29
	v_lshl_add_u64 v[196:197], s[50:51], 0, v[160:161]
	global_load_lds_dwordx4 v[174:175], off
	s_add_i32 m0, s29, 0x2000
	s_nop 0
	global_load_lds_dwordx4 v[196:197], off
	s_barrier
	s_waitcnt lgkmcnt(3)
	v_mfma_f32_16x16x32_bf16 v[120:123], v[206:209], v[144:147], v[120:123]
	s_waitcnt lgkmcnt(1)
	v_mfma_f32_16x16x32_bf16 v[112:115], v[214:217], v[144:147], v[112:115]
	v_mfma_f32_16x16x32_bf16 v[104:107], v[206:209], v[152:155], v[104:107]
	v_mfma_f32_16x16x32_bf16 v[96:99], v[214:217], v[152:155], v[96:99]
	v_mfma_f32_16x16x32_bf16 v[88:91], v[206:209], v[170:173], v[88:91]
	v_mfma_f32_16x16x32_bf16 v[80:83], v[214:217], v[170:173], v[80:83]
	v_mfma_f32_16x16x32_bf16 v[72:75], v[206:209], v[192:195], v[72:75]
	v_mfma_f32_16x16x32_bf16 v[64:67], v[214:217], v[192:195], v[64:67]
	v_mfma_f32_16x16x32_bf16 v[120:123], v[210:213], v[148:151], v[120:123]
	s_waitcnt lgkmcnt(0)
	v_mfma_f32_16x16x32_bf16 v[112:115], v[232:235], v[148:151], v[112:115]
	v_mfma_f32_16x16x32_bf16 v[104:107], v[210:213], v[166:169], v[104:107]
	v_mfma_f32_16x16x32_bf16 v[96:99], v[232:235], v[166:169], v[96:99]
	v_mfma_f32_16x16x32_bf16 v[88:91], v[210:213], v[188:191], v[88:91]
	v_mfma_f32_16x16x32_bf16 v[80:83], v[232:235], v[188:191], v[80:83]
	v_mfma_f32_16x16x32_bf16 v[72:75], v[210:213], v[202:205], v[72:75]
	v_mfma_f32_16x16x32_bf16 v[64:67], v[232:235], v[202:205], v[64:67]
	s_mov_b32 m0, s56
	v_lshl_add_u64 v[236:237], s[52:53], 0, v[156:157]
	s_barrier
	ds_read_b128 v[144:147], v201 offset:16384
	ds_read_b128 v[152:155], v201 offset:18432
	ds_read_b128 v[170:173], v201 offset:20480
	ds_read_b128 v[192:195], v201 offset:22528
	ds_read_b128 v[148:151], v201 offset:17408
	ds_read_b128 v[166:169], v201 offset:19456
	ds_read_b128 v[188:191], v201 offset:21504
	ds_read_b128 v[202:205], v201 offset:23552
	global_load_lds_dwordx4 v[236:237], off
	v_lshl_add_u64 v[238:239], s[52:53], 0, v[158:159]
	s_mov_b32 m0, s57
	s_nop 0
	global_load_lds_dwordx4 v[238:239], off
	s_barrier
	s_waitcnt lgkmcnt(7)
	v_mfma_f32_16x16x32_bf16 v[60:63], v[128:131], v[144:147], v[60:63]
	v_mfma_f32_16x16x32_bf16 v[52:55], v[136:139], v[144:147], v[52:55]
	s_waitcnt lgkmcnt(6)
	v_mfma_f32_16x16x32_bf16 v[44:47], v[128:131], v[152:155], v[44:47]
	v_mfma_f32_16x16x32_bf16 v[36:39], v[136:139], v[152:155], v[36:39]
	s_waitcnt lgkmcnt(5)
	v_mfma_f32_16x16x32_bf16 v[28:31], v[128:131], v[170:173], v[28:31]
	v_mfma_f32_16x16x32_bf16 v[20:23], v[136:139], v[170:173], v[20:23]
	s_waitcnt lgkmcnt(4)
	v_mfma_f32_16x16x32_bf16 v[12:15], v[128:131], v[192:195], v[12:15]
	v_mfma_f32_16x16x32_bf16 v[4:7], v[136:139], v[192:195], v[4:7]
	s_waitcnt lgkmcnt(3)
	v_mfma_f32_16x16x32_bf16 v[60:63], v[132:135], v[148:151], v[60:63]
	v_mfma_f32_16x16x32_bf16 v[52:55], v[140:143], v[148:151], v[52:55]
	s_waitcnt lgkmcnt(2)
	v_mfma_f32_16x16x32_bf16 v[44:47], v[132:135], v[166:169], v[44:47]
	v_mfma_f32_16x16x32_bf16 v[36:39], v[140:143], v[166:169], v[36:39]
	s_waitcnt lgkmcnt(1)
	v_mfma_f32_16x16x32_bf16 v[28:31], v[132:135], v[188:191], v[28:31]
	v_mfma_f32_16x16x32_bf16 v[20:23], v[140:143], v[188:191], v[20:23]
	s_waitcnt lgkmcnt(0)
	v_mfma_f32_16x16x32_bf16 v[12:15], v[132:135], v[202:205], v[12:15]
	v_mfma_f32_16x16x32_bf16 v[4:7], v[140:143], v[202:205], v[4:7]
	s_barrier
	s_add_u32 s72, s50, 0x40000
	s_addc_u32 s73, s51, 0
	s_add_i32 s28, s28, s55
	v_lshl_add_u64 v[128:129], s[72:73], 0, v[176:177]
	s_mov_b32 m0, s28
	s_nop 0
	global_load_lds_dwordx4 v[128:129], off
	v_lshl_add_u64 v[128:129], s[72:73], 0, v[160:161]
	s_add_i32 m0, s28, 0x2000
	s_nop 0
	global_load_lds_dwordx4 v[128:129], off
	s_waitcnt vmcnt(6)
	s_barrier
	v_mfma_f32_16x16x32_bf16 v[56:59], v[206:209], v[144:147], v[56:59]
	v_mfma_f32_16x16x32_bf16 v[48:51], v[214:217], v[144:147], v[48:51]
	v_mfma_f32_16x16x32_bf16 v[40:43], v[206:209], v[152:155], v[40:43]
	v_mfma_f32_16x16x32_bf16 v[32:35], v[214:217], v[152:155], v[32:35]
	v_mfma_f32_16x16x32_bf16 v[24:27], v[206:209], v[170:173], v[24:27]
	v_mfma_f32_16x16x32_bf16 v[16:19], v[214:217], v[170:173], v[16:19]
	v_mfma_f32_16x16x32_bf16 v[8:11], v[206:209], v[192:195], v[8:11]
	v_mfma_f32_16x16x32_bf16 v[0:3], v[214:217], v[192:195], v[0:3]
	v_mfma_f32_16x16x32_bf16 v[56:59], v[210:213], v[148:151], v[56:59]
	v_mfma_f32_16x16x32_bf16 v[48:51], v[232:235], v[148:151], v[48:51]
	v_mfma_f32_16x16x32_bf16 v[40:43], v[210:213], v[166:169], v[40:43]
	v_mfma_f32_16x16x32_bf16 v[32:35], v[232:235], v[166:169], v[32:35]
	v_mfma_f32_16x16x32_bf16 v[24:27], v[210:213], v[188:191], v[24:27]
	v_mfma_f32_16x16x32_bf16 v[16:19], v[232:235], v[188:191], v[16:19]
	v_mfma_f32_16x16x32_bf16 v[8:11], v[210:213], v[202:205], v[8:11]
	v_mfma_f32_16x16x32_bf16 v[0:3], v[232:235], v[202:205], v[0:3]
	s_add_i32 s28, 0, 0x18000
	v_add_u32_e32 v140, s28, v200
	s_barrier
	ds_read_b128 v[128:131], v140
	ds_read_b128 v[132:135], v140 offset:1024
	ds_read_b128 v[136:139], v140 offset:2048
	ds_read_b128 v[140:143], v140 offset:3072
	s_add_u32 s52, s52, 0x40000
	s_addc_u32 s53, s53, 0
	s_mov_b32 m0, s58
	v_lshl_add_u64 v[206:207], s[52:53], 0, v[156:157]
	ds_read_b128 v[144:147], v201 offset:32768
	ds_read_b128 v[152:155], v201 offset:34816
	ds_read_b128 v[170:173], v201 offset:36864
	ds_read_b128 v[192:195], v201 offset:38912
	ds_read_b128 v[148:151], v201 offset:33792
	ds_read_b128 v[166:169], v201 offset:35840
	ds_read_b128 v[188:191], v201 offset:37888
	ds_read_b128 v[202:205], v201 offset:39936
	global_load_lds_dwordx4 v[206:207], off
	v_lshl_add_u64 v[206:207], s[52:53], 0, v[158:159]
	s_mov_b32 m0, s59
	s_nop 0
	global_load_lds_dwordx4 v[206:207], off
	s_waitcnt lgkmcnt(8)
	s_barrier
	s_waitcnt lgkmcnt(7)
	v_mfma_f32_16x16x32_bf16 v[124:127], v[128:131], v[144:147], v[124:127]
	v_mfma_f32_16x16x32_bf16 v[116:119], v[136:139], v[144:147], v[116:119]
	s_waitcnt lgkmcnt(6)
	v_mfma_f32_16x16x32_bf16 v[108:111], v[128:131], v[152:155], v[108:111]
	v_mfma_f32_16x16x32_bf16 v[100:103], v[136:139], v[152:155], v[100:103]
	s_waitcnt lgkmcnt(5)
	v_mfma_f32_16x16x32_bf16 v[92:95], v[128:131], v[170:173], v[92:95]
	v_mfma_f32_16x16x32_bf16 v[84:87], v[136:139], v[170:173], v[84:87]
	s_waitcnt lgkmcnt(4)
	v_mfma_f32_16x16x32_bf16 v[76:79], v[128:131], v[192:195], v[76:79]
	v_mfma_f32_16x16x32_bf16 v[68:71], v[136:139], v[192:195], v[68:71]
	s_waitcnt lgkmcnt(3)
	v_mfma_f32_16x16x32_bf16 v[124:127], v[132:135], v[148:151], v[124:127]
	v_mfma_f32_16x16x32_bf16 v[116:119], v[140:143], v[148:151], v[116:119]
	s_waitcnt lgkmcnt(2)
	v_mfma_f32_16x16x32_bf16 v[108:111], v[132:135], v[166:169], v[108:111]
	v_mfma_f32_16x16x32_bf16 v[100:103], v[140:143], v[166:169], v[100:103]
	s_waitcnt lgkmcnt(1)
	v_mfma_f32_16x16x32_bf16 v[92:95], v[132:135], v[188:191], v[92:95]
	v_mfma_f32_16x16x32_bf16 v[84:87], v[140:143], v[188:191], v[84:87]
	s_waitcnt lgkmcnt(0)
	v_mfma_f32_16x16x32_bf16 v[76:79], v[132:135], v[202:205], v[76:79]
	v_mfma_f32_16x16x32_bf16 v[68:71], v[140:143], v[202:205], v[68:71]
	s_barrier
	s_add_i32 s29, 0, 0x1c000
	s_add_i32 s28, s28, s55
	v_add_u32_e32 v232, s29, v200
	v_lshl_add_u64 v[174:175], v[174:175], 0, s[40:41]
	s_mov_b32 m0, s28
	ds_read_b128 v[206:209], v232
	ds_read_b128 v[210:213], v232 offset:1024
	ds_read_b128 v[214:217], v232 offset:2048
	ds_read_b128 v[232:235], v232 offset:3072
	global_load_lds_dwordx4 v[174:175], off
	v_lshl_add_u64 v[174:175], v[196:197], 0, s[40:41]
	s_add_i32 m0, s28, 0x2000
	s_nop 0
	global_load_lds_dwordx4 v[174:175], off
	s_barrier
	s_waitcnt lgkmcnt(3)
	v_mfma_f32_16x16x32_bf16 v[120:123], v[206:209], v[144:147], v[120:123]
	s_waitcnt lgkmcnt(1)
	v_mfma_f32_16x16x32_bf16 v[112:115], v[214:217], v[144:147], v[112:115]
	v_mfma_f32_16x16x32_bf16 v[104:107], v[206:209], v[152:155], v[104:107]
	v_mfma_f32_16x16x32_bf16 v[96:99], v[214:217], v[152:155], v[96:99]
	v_mfma_f32_16x16x32_bf16 v[88:91], v[206:209], v[170:173], v[88:91]
	v_mfma_f32_16x16x32_bf16 v[80:83], v[214:217], v[170:173], v[80:83]
	v_mfma_f32_16x16x32_bf16 v[72:75], v[206:209], v[192:195], v[72:75]
	v_mfma_f32_16x16x32_bf16 v[64:67], v[214:217], v[192:195], v[64:67]
	v_mfma_f32_16x16x32_bf16 v[120:123], v[210:213], v[148:151], v[120:123]
	s_waitcnt lgkmcnt(0)
	v_mfma_f32_16x16x32_bf16 v[112:115], v[232:235], v[148:151], v[112:115]
	v_mfma_f32_16x16x32_bf16 v[104:107], v[210:213], v[166:169], v[104:107]
	v_mfma_f32_16x16x32_bf16 v[96:99], v[232:235], v[166:169], v[96:99]
	v_mfma_f32_16x16x32_bf16 v[88:91], v[210:213], v[188:191], v[88:91]
	v_mfma_f32_16x16x32_bf16 v[80:83], v[232:235], v[188:191], v[80:83]
	v_mfma_f32_16x16x32_bf16 v[72:75], v[210:213], v[202:205], v[72:75]
	v_mfma_f32_16x16x32_bf16 v[64:67], v[232:235], v[202:205], v[64:67]
	s_mov_b32 m0, s62
	v_lshl_add_u64 v[174:175], v[236:237], 0, s[40:41]
	s_barrier
	ds_read_b128 v[144:147], v201 offset:49152
	ds_read_b128 v[152:155], v201 offset:51200
	ds_read_b128 v[170:173], v201 offset:53248
	ds_read_b128 v[192:195], v201 offset:55296
	ds_read_b128 v[148:151], v201 offset:50176
	ds_read_b128 v[166:169], v201 offset:52224
	ds_read_b128 v[188:191], v201 offset:54272
	ds_read_b128 v[202:205], v201 offset:56320
	global_load_lds_dwordx4 v[174:175], off
	v_lshl_add_u64 v[174:175], v[238:239], 0, s[40:41]
	s_mov_b32 m0, s63
	s_nop 0
	global_load_lds_dwordx4 v[174:175], off
	s_barrier
	s_waitcnt lgkmcnt(7)
	v_mfma_f32_16x16x32_bf16 v[60:63], v[128:131], v[144:147], v[60:63]
	v_mfma_f32_16x16x32_bf16 v[52:55], v[136:139], v[144:147], v[52:55]
	s_waitcnt lgkmcnt(6)
	v_mfma_f32_16x16x32_bf16 v[44:47], v[128:131], v[152:155], v[44:47]
	v_mfma_f32_16x16x32_bf16 v[36:39], v[136:139], v[152:155], v[36:39]
	s_waitcnt lgkmcnt(5)
	v_mfma_f32_16x16x32_bf16 v[28:31], v[128:131], v[170:173], v[28:31]
	v_mfma_f32_16x16x32_bf16 v[20:23], v[136:139], v[170:173], v[20:23]
	s_waitcnt lgkmcnt(4)
	v_mfma_f32_16x16x32_bf16 v[12:15], v[128:131], v[192:195], v[12:15]
	v_mfma_f32_16x16x32_bf16 v[4:7], v[136:139], v[192:195], v[4:7]
	s_waitcnt lgkmcnt(3)
	v_mfma_f32_16x16x32_bf16 v[60:63], v[132:135], v[148:151], v[60:63]
	v_mfma_f32_16x16x32_bf16 v[52:55], v[140:143], v[148:151], v[52:55]
	s_waitcnt lgkmcnt(2)
	v_mfma_f32_16x16x32_bf16 v[44:47], v[132:135], v[166:169], v[44:47]
	v_mfma_f32_16x16x32_bf16 v[36:39], v[140:143], v[166:169], v[36:39]
	s_waitcnt lgkmcnt(1)
	v_mfma_f32_16x16x32_bf16 v[28:31], v[132:135], v[188:191], v[28:31]
	v_mfma_f32_16x16x32_bf16 v[20:23], v[140:143], v[188:191], v[20:23]
	s_waitcnt lgkmcnt(0)
	v_mfma_f32_16x16x32_bf16 v[12:15], v[132:135], v[202:205], v[12:15]
	v_mfma_f32_16x16x32_bf16 v[4:7], v[140:143], v[202:205], v[4:7]
	s_barrier
	s_add_u32 s50, s50, 0x40080
	s_addc_u32 s51, s51, 0
	s_add_i32 s28, s29, s55
	v_lshl_add_u64 v[128:129], s[50:51], 0, v[176:177]
	s_mov_b32 m0, s28
	s_nop 0
	global_load_lds_dwordx4 v[128:129], off
	v_lshl_add_u64 v[128:129], s[50:51], 0, v[160:161]
	s_add_i32 m0, s28, 0x2000
	s_nop 0
	global_load_lds_dwordx4 v[128:129], off
	s_waitcnt vmcnt(6)
	s_barrier
	v_mfma_f32_16x16x32_bf16 v[56:59], v[206:209], v[144:147], v[56:59]
	v_mfma_f32_16x16x32_bf16 v[48:51], v[214:217], v[144:147], v[48:51]
	v_mfma_f32_16x16x32_bf16 v[40:43], v[206:209], v[152:155], v[40:43]
	v_mfma_f32_16x16x32_bf16 v[32:35], v[214:217], v[152:155], v[32:35]
	v_mfma_f32_16x16x32_bf16 v[24:27], v[206:209], v[170:173], v[24:27]
	v_mfma_f32_16x16x32_bf16 v[16:19], v[214:217], v[170:173], v[16:19]
	v_mfma_f32_16x16x32_bf16 v[8:11], v[206:209], v[192:195], v[8:11]
	v_mfma_f32_16x16x32_bf16 v[0:3], v[214:217], v[192:195], v[0:3]
	v_mfma_f32_16x16x32_bf16 v[56:59], v[210:213], v[148:151], v[56:59]
	v_mfma_f32_16x16x32_bf16 v[48:51], v[232:235], v[148:151], v[48:51]
	v_mfma_f32_16x16x32_bf16 v[40:43], v[210:213], v[166:169], v[40:43]
	v_mfma_f32_16x16x32_bf16 v[32:35], v[232:235], v[166:169], v[32:35]
	v_mfma_f32_16x16x32_bf16 v[24:27], v[210:213], v[188:191], v[24:27]
	v_mfma_f32_16x16x32_bf16 v[16:19], v[232:235], v[188:191], v[16:19]
	v_mfma_f32_16x16x32_bf16 v[8:11], v[210:213], v[202:205], v[8:11]
	v_mfma_f32_16x16x32_bf16 v[0:3], v[232:235], v[202:205], v[0:3]
	s_add_i32 s70, s70, 2
	s_add_u32 s6, s6, 0x100
	s_addc_u32 s7, s7, 0
	s_add_u32 s68, s68, 0x100
	s_addc_u32 s69, s69, 0
	s_cmp_lt_u32 s70, 14
	s_barrier
	s_cbranch_scc1 .LBB0_1436
	v_mov_b32_e32 v134, v199
	v_mov_b32_e32 v128, v198
	s_lshl_b32 s4, s4, 8
	s_add_i32 s4, s4, s60
	v_add_u32_e32 v192, s4, v128
	v_lshlrev_b32_e32 v128, 2, v134
	v_ashrrev_i32_e32 v129, 31, v128
	v_ashrrev_i32_e32 v193, 31, v192
	v_add_u32_e32 v190, 16, v192
	v_lshl_add_u64 v[132:133], v[128:129], 2, s[8:9]
	v_lshlrev_b64 v[128:129], 6, v[192:193]
	v_ashrrev_i32_e32 v191, 31, v190
	v_add_u32_e32 v188, 32, v192
	v_lshl_add_u64 v[128:129], v[132:133], 0, v[128:129]
	v_lshlrev_b64 v[130:131], 6, v[190:191]
	v_ashrrev_i32_e32 v189, 31, v188
	v_lshl_add_u64 v[130:131], v[132:133], 0, v[130:131]
	v_add_u32_e32 v244, s60, v198
	v_lshlrev_b32_e32 v244, 6, v244
	v_lshl_add_u32 v244, v199, 4, v244
	v_add_u32_e32 v244, 0x20010, v244
	ds_read_b128 v[202:205], v244 offset:0
	ds_read_b128 v[144:147], v244 offset:1024
	v_lshlrev_b64 v[128:129], 6, v[188:189]
	v_add_u32_e32 v174, 48, v192
	v_lshl_add_u64 v[128:129], v[132:133], 0, v[128:129]
	v_ashrrev_i32_e32 v175, 31, v174
	ds_read_b128 v[148:151], v244 offset:2048
	v_lshlrev_b64 v[128:129], 6, v[174:175]
	v_lshl_add_u64 v[128:129], v[132:133], 0, v[128:129]
	ds_read_b128 v[152:155], v244 offset:3072
	v_add_u32_e32 v172, 0x80, v192
	v_ashrrev_i32_e32 v173, 31, v172
	v_lshlrev_b64 v[128:129], 6, v[172:173]
	v_lshl_add_u64 v[128:129], v[132:133], 0, v[128:129]
	ds_read_b128 v[140:143], v244 offset:8192
	v_add_u32_e32 v170, 0x90, v192
	v_ashrrev_i32_e32 v171, 31, v170
	v_lshlrev_b64 v[128:129], 6, v[170:171]
	v_lshl_add_u64 v[128:129], v[132:133], 0, v[128:129]
	ds_read_b128 v[128:131], v244 offset:9216
	s_lshl_b32 s5, s5, 7
	v_add_u32_e32 v168, 0xa0, v192
	v_add_u32_e32 v166, 0xb0, v192
	s_or_b32 s5, s5, s61
	v_ashrrev_i32_e32 v169, 31, v168
	v_ashrrev_i32_e32 v167, 31, v166
	v_lshl_add_u32 v194, v134, 3, s5
	v_lshlrev_b64 v[134:135], 6, v[168:169]
	v_lshlrev_b64 v[136:137], 6, v[166:167]
	v_lshl_add_u64 v[134:135], v[132:133], 0, v[134:135]
	v_lshl_add_u64 v[132:133], v[132:133], 0, v[136:137]
	ds_read_b128 v[136:139], v244 offset:10240
	s_nop 0
	ds_read_b128 v[132:135], v244 offset:11264
	s_mov_b32 s4, 0x358637bd
	v_mov_b64_e32 v[196:197], s[4:5]
	v_ashrrev_i32_e32 v195, 31, v194
	s_mov_b64 s[50:51], s[20:21]
	s_waitcnt lgkmcnt(0)
	v_mov_b32_e32 v206, v203
	v_mov_b32_e32 v207, v204
	v_mov_b32_e32 v203, v205
	v_mov_b32_e32 v204, v145
	v_mov_b32_e32 v205, v146
	v_mov_b32_e32 v145, v147
	v_pk_add_f32 v[202:203], v[206:207], v[202:203]
	v_mov_b32_e32 v146, v149
	v_mov_b32_e32 v147, v150
	v_mov_b32_e32 v149, v151
	v_mov_b32_e32 v150, v153
	v_mov_b32_e32 v151, v154
	v_mov_b32_e32 v153, v155
	v_pk_add_f32 v[144:145], v[204:205], v[144:145]
	v_mov_b32_e32 v155, v202
	v_pk_add_f32 v[146:147], v[146:147], v[148:149]
	v_pk_add_f32 v[148:149], v[150:151], v[152:153]
	v_mov_b32_e32 v154, v144
	v_mov_b32_e32 v202, v145
	v_mov_b32_e32 v144, v148
	v_mov_b32_e32 v145, v146
	v_mov_b32_e32 v146, v149
	v_pk_add_f32 v[148:149], v[154:155], v[202:203]
	v_pk_add_f32 v[144:145], v[144:145], v[146:147]
	ds_bpermute_b32 v147, v219, v149
	ds_bpermute_b32 v146, v219, v148
	ds_bpermute_b32 v151, v219, v145
	ds_bpermute_b32 v150, v219, v144
	v_mov_b32_e32 v152, v141
	v_mov_b32_e32 v153, v142
	v_mov_b32_e32 v141, v143
	s_waitcnt lgkmcnt(0)
	v_pk_add_f32 v[142:143], v[148:149], v[146:147]
	ds_bpermute_b32 v147, v218, v143
	ds_bpermute_b32 v146, v218, v142
	v_pk_add_f32 v[144:145], v[144:145], v[150:151]
	ds_bpermute_b32 v149, v218, v145
	ds_bpermute_b32 v148, v218, v144
	v_mov_b32_e32 v150, v129
	s_waitcnt lgkmcnt(2)
	v_pk_add_f32 v[142:143], v[142:143], v[146:147]
	v_mov_b32_e32 v151, v130
	v_pk_fma_f32 v[142:143], v[142:143], s[30:31], v[196:197] op_sel_hi:[1,0,0]
	s_waitcnt lgkmcnt(0)
	v_pk_add_f32 v[144:145], v[144:145], v[148:149]
	v_mul_f32_e32 v129, 0x4b800000, v143
	v_cmp_gt_f32_e32 vcc, s86, v143
	v_pk_fma_f32 v[146:147], v[144:145], s[30:31], v[196:197] op_sel_hi:[1,0,0]
	v_mul_f32_e32 v130, 0x4b800000, v142
	v_cndmask_b32_e32 v129, v143, v129, vcc
	v_rsq_f32_e32 v129, v129
	v_cmp_gt_f32_e64 s[4:5], s86, v142
	v_mul_f32_e32 v144, 0x4b800000, v147
	v_cmp_gt_f32_e64 s[6:7], s86, v147
	v_cndmask_b32_e64 v130, v142, v130, s[4:5]
	v_rsq_f32_e32 v142, v130
	v_cndmask_b32_e64 v130, v147, v144, s[6:7]
	v_rsq_f32_e32 v143, v130
	v_mul_f32_e32 v130, 0x45800000, v129
	v_cndmask_b32_e32 v144, v129, v130, vcc
	v_mov_b32_e32 v129, v131
	v_pk_add_f32 v[140:141], v[152:153], v[140:141]
	v_pk_add_f32 v[128:129], v[150:151], v[128:129]
	v_mov_b32_e32 v131, v140
	v_mov_b32_e32 v130, v128
	v_mov_b32_e32 v140, v129
	v_pk_add_f32 v[128:129], v[130:131], v[140:141]
	ds_bpermute_b32 v131, v219, v129
	ds_bpermute_b32 v130, v219, v128
	v_mul_f32_e32 v145, 0x45800000, v142
	v_cndmask_b32_e64 v142, v142, v145, s[4:5]
	v_mul_f32_e32 v140, 0x4b800000, v146
	v_cmp_gt_f32_e32 vcc, s86, v146
	s_waitcnt lgkmcnt(0)
	v_pk_add_f32 v[128:129], v[128:129], v[130:131]
	ds_bpermute_b32 v131, v218, v129
	ds_bpermute_b32 v130, v218, v128
	v_cndmask_b32_e32 v140, v146, v140, vcc
	v_rsq_f32_e32 v141, v140
	v_mul_f32_e32 v140, 0x45800000, v143
	v_cndmask_b32_e64 v140, v143, v140, s[6:7]
	s_waitcnt lgkmcnt(0)
	v_pk_add_f32 v[128:129], v[128:129], v[130:131]
	v_mov_b32_e32 v131, v138
	v_pk_fma_f32 v[128:129], v[128:129], s[30:31], v[196:197] op_sel_hi:[1,0,0]
	v_mul_f32_e32 v143, 0x45800000, v141
	v_mul_f32_e32 v130, 0x4b800000, v129
	v_cmp_gt_f32_e64 s[4:5], s86, v129
	v_cmp_gt_f32_e64 s[6:7], s86, v128
	v_pk_mul_f32 v[110:111], v[110:111], v[142:143] op_sel_hi:[1,0]
	v_cndmask_b32_e64 v129, v129, v130, s[4:5]
	v_mov_b32_e32 v130, v137
	v_mov_b32_e32 v137, v139
	v_pk_add_f32 v[130:131], v[130:131], v[136:137]
	v_mov_b32_e32 v136, v133
	v_mov_b32_e32 v137, v134
	v_mov_b32_e32 v133, v135
	v_pk_add_f32 v[132:133], v[136:137], v[132:133]
	v_mov_b32_e32 v135, v130
	v_mov_b32_e32 v134, v132
	v_mov_b32_e32 v130, v133
	v_pk_add_f32 v[130:131], v[134:135], v[130:131]
	ds_bpermute_b32 v133, v219, v131
	ds_bpermute_b32 v132, v219, v130
	v_rsq_f32_e32 v145, v129
	v_mul_f32_e32 v129, 0x4b800000, v128
	v_cndmask_b32_e64 v128, v128, v129, s[6:7]
	v_rsq_f32_e32 v135, v128
	s_waitcnt lgkmcnt(0)
	v_pk_add_f32 v[128:129], v[130:131], v[132:133]
	ds_bpermute_b32 v131, v218, v129
	ds_bpermute_b32 v130, v218, v128
	v_pk_mul_f32 v[126:127], v[126:127], v[144:145] op_sel_hi:[1,0]
	v_pk_mul_f32 v[122:123], v[122:123], v[144:145] op_sel_hi:[1,0]
	v_pk_mul_f32 v[116:117], v[116:117], v[144:145] op_sel_hi:[1,0]
	v_pk_mul_f32 v[124:125], v[124:125], v[144:145] op_sel_hi:[1,0]
	v_pk_mul_f32 v[138:139], v[126:127], s[44:45] op_sel_hi:[1,0]
	v_pk_mul_f32 v[120:121], v[120:121], v[144:145] op_sel_hi:[1,0]
	v_pk_mul_f32 v[122:123], v[126:127], v[122:123]
	v_pk_mul_f32 v[118:119], v[118:119], v[144:145] op_sel_hi:[1,0]
	v_pk_mul_f32 v[126:127], v[116:117], s[44:45] op_sel_hi:[1,0]
	v_pk_mul_f32 v[146:147], v[124:125], s[44:45] op_sel_hi:[1,0]
	v_pk_mul_f32 v[120:121], v[124:125], v[120:121]
	v_pk_mul_f32 v[124:125], v[118:119], s[44:45] op_sel_hi:[1,0]
	v_exp_f32_e32 v126, v126
	v_exp_f32_e32 v127, v127
	s_waitcnt lgkmcnt(0)
	v_pk_add_f32 v[128:129], v[128:129], v[130:131]
	v_exp_f32_e32 v146, v146
	v_exp_f32_e32 v138, v138
	v_exp_f32_e32 v139, v139
	v_exp_f32_e32 v147, v147
	v_exp_f32_e32 v124, v124
	v_exp_f32_e32 v125, v125
	v_pk_fma_f32 v[128:129], v[128:129], s[30:31], v[196:197] op_sel_hi:[1,0,0]
	v_cndmask_b32_e32 v136, v141, v143, vcc
	v_mul_f32_e32 v132, 0x45800000, v145
	v_mul_f32_e32 v130, 0x4b800000, v129
	v_cmp_gt_f32_e32 vcc, s86, v129
	v_cndmask_b32_e64 v134, v145, v132, s[4:5]
	v_cmp_gt_f32_e64 s[4:5], s86, v128
	v_cndmask_b32_e32 v129, v129, v130, vcc
	v_mul_f32_e32 v130, 0x4b800000, v128
	v_pk_add_f32 v[126:127], v[126:127], 1.0 op_sel_hi:[1,0]
	v_rsq_f32_e32 v129, v129
	v_cndmask_b32_e64 v128, v128, v130, s[4:5]
	v_pk_add_f32 v[138:139], v[138:139], 1.0 op_sel_hi:[1,0]
	v_pk_add_f32 v[146:147], v[146:147], 1.0 op_sel_hi:[1,0]
	v_pk_add_f32 v[124:125], v[124:125], 1.0 op_sel_hi:[1,0]
	v_rcp_f32_e32 v126, v126
	v_rcp_f32_e32 v127, v127
	v_rsq_f32_e32 v128, v128
	v_rcp_f32_e32 v146, v146
	v_rcp_f32_e32 v138, v138
	v_rcp_f32_e32 v139, v139
	v_rcp_f32_e32 v147, v147
	v_rcp_f32_e32 v124, v124
	v_rcp_f32_e32 v125, v125
	v_pk_mul_f32 v[112:113], v[112:113], v[144:145] op_sel_hi:[1,0]
	v_pk_mul_f32 v[114:115], v[114:115], v[144:145] op_sel_hi:[1,0]
	v_pk_mul_f32 v[112:113], v[116:117], v[112:113]
	v_mul_f32_e32 v130, 0x45800000, v129
	v_pk_mul_f32 v[114:115], v[118:119], v[114:115]
	v_pk_mul_f32 v[112:113], v[112:113], v[126:127]
	v_cndmask_b32_e32 v130, v129, v130, vcc
	v_mul_f32_e32 v129, 0x45800000, v128
	v_pk_mul_f32 v[122:123], v[122:123], v[138:139]
	v_pk_mul_f32 v[120:121], v[120:121], v[146:147]
	v_pk_mul_f32 v[114:115], v[114:115], v[124:125]
	v_cvt_pk_bf16_f32 v116, v120, v121
	v_cvt_pk_bf16_f32 v117, v122, v123
	v_cvt_pk_bf16_f32 v118, v112, v113
	v_mov_b64_e32 v[112:113], s[10:11]
	v_cndmask_b32_e64 v128, v128, v129, s[4:5]
	v_cvt_pk_bf16_f32 v119, v114, v115
	v_mad_i64_i32 v[120:121], s[4:5], v192, s35, v[112:113]
	v_lshlrev_b64 v[114:115], 1, v[194:195]
	v_lshl_add_u64 v[120:121], v[120:121], 0, v[114:115]
	v_pk_mul_f32 v[108:109], v[108:109], v[142:143] op_sel_hi:[1,0]
	v_pk_mul_f32 v[106:107], v[106:107], v[142:143] op_sel_hi:[1,0]
	v_pk_mul_f32 v[104:105], v[104:105], v[142:143] op_sel_hi:[1,0]
	v_pk_mul_f32 v[102:103], v[102:103], v[142:143] op_sel_hi:[1,0]
	v_pk_mul_f32 v[100:101], v[100:101], v[142:143] op_sel_hi:[1,0]
	global_store_dwordx4 v[120:121], v[116:119], off
	v_pk_mul_f32 v[104:105], v[108:109], v[104:105]
	v_pk_mul_f32 v[106:107], v[110:111], v[106:107]
	v_pk_mul_f32 v[116:117], v[110:111], s[44:45] op_sel_hi:[1,0]
	v_pk_mul_f32 v[118:119], v[108:109], s[44:45] op_sel_hi:[1,0]
	v_pk_mul_f32 v[108:109], v[102:103], s[44:45] op_sel_hi:[1,0]
	v_pk_mul_f32 v[110:111], v[100:101], s[44:45] op_sel_hi:[1,0]
	v_exp_f32_e32 v108, v108
	v_exp_f32_e32 v110, v110
	v_exp_f32_e32 v109, v109
	v_exp_f32_e32 v111, v111
	v_exp_f32_e32 v118, v118
	v_exp_f32_e32 v116, v116
	v_exp_f32_e32 v117, v117
	v_exp_f32_e32 v119, v119
	v_pk_add_f32 v[108:109], v[108:109], 1.0 op_sel_hi:[1,0]
	v_pk_add_f32 v[110:111], v[110:111], 1.0 op_sel_hi:[1,0]
	v_pk_add_f32 v[116:117], v[116:117], 1.0 op_sel_hi:[1,0]
	v_pk_add_f32 v[118:119], v[118:119], 1.0 op_sel_hi:[1,0]
	v_rcp_f32_e32 v110, v110
	v_rcp_f32_e32 v108, v108
	v_rcp_f32_e32 v109, v109
	v_rcp_f32_e32 v111, v111
	v_rcp_f32_e32 v118, v118
	v_rcp_f32_e32 v116, v116
	v_rcp_f32_e32 v117, v117
	v_rcp_f32_e32 v119, v119
	v_pk_mul_f32 v[98:99], v[98:99], v[142:143] op_sel_hi:[1,0]
	v_pk_mul_f32 v[96:97], v[96:97], v[142:143] op_sel_hi:[1,0]
	v_pk_mul_f32 v[98:99], v[102:103], v[98:99]
	v_pk_mul_f32 v[96:97], v[100:101], v[96:97]
	v_pk_mul_f32 v[100:101], v[98:99], v[108:109]
	v_pk_mul_f32 v[98:99], v[96:97], v[110:111]
	v_pk_mul_f32 v[106:107], v[106:107], v[116:117]
	v_pk_mul_f32 v[104:105], v[104:105], v[118:119]
	v_pk_mul_f32 v[94:95], v[94:95], v[140:141] op_sel_hi:[1,0]
	v_cvt_pk_bf16_f32 v96, v104, v105
	v_cvt_pk_bf16_f32 v97, v106, v107
	v_cvt_pk_bf16_f32 v98, v98, v99
	v_cvt_pk_bf16_f32 v99, v100, v101
	v_mad_i64_i32 v[100:101], s[4:5], v190, s35, v[112:113]
	v_lshl_add_u64 v[100:101], v[100:101], 0, v[114:115]
	v_pk_mul_f32 v[92:93], v[92:93], v[140:141] op_sel_hi:[1,0]
	v_pk_mul_f32 v[90:91], v[90:91], v[140:141] op_sel_hi:[1,0]
	v_pk_mul_f32 v[88:89], v[88:89], v[140:141] op_sel_hi:[1,0]
	v_pk_mul_f32 v[86:87], v[86:87], v[140:141] op_sel_hi:[1,0]
	v_pk_mul_f32 v[84:85], v[84:85], v[140:141] op_sel_hi:[1,0]
	global_store_dwordx4 v[100:101], v[96:99], off
	v_pk_mul_f32 v[88:89], v[92:93], v[88:89]
	v_pk_mul_f32 v[90:91], v[94:95], v[90:91]
	v_pk_mul_f32 v[96:97], v[94:95], s[44:45] op_sel_hi:[1,0]
	v_pk_mul_f32 v[98:99], v[92:93], s[44:45] op_sel_hi:[1,0]
	v_pk_mul_f32 v[92:93], v[86:87], s[44:45] op_sel_hi:[1,0]
	v_pk_mul_f32 v[94:95], v[84:85], s[44:45] op_sel_hi:[1,0]
	v_exp_f32_e32 v92, v92
	v_exp_f32_e32 v94, v94
	v_exp_f32_e32 v93, v93
	v_exp_f32_e32 v95, v95
	v_exp_f32_e32 v98, v98
	v_exp_f32_e32 v96, v96
	v_exp_f32_e32 v97, v97
	v_exp_f32_e32 v99, v99
	v_pk_add_f32 v[92:93], v[92:93], 1.0 op_sel_hi:[1,0]
	v_pk_add_f32 v[94:95], v[94:95], 1.0 op_sel_hi:[1,0]
	v_pk_add_f32 v[96:97], v[96:97], 1.0 op_sel_hi:[1,0]
	v_pk_add_f32 v[98:99], v[98:99], 1.0 op_sel_hi:[1,0]
	v_rcp_f32_e32 v94, v94
	v_rcp_f32_e32 v92, v92
	v_rcp_f32_e32 v93, v93
	v_rcp_f32_e32 v95, v95
	v_rcp_f32_e32 v98, v98
	v_rcp_f32_e32 v96, v96
	v_rcp_f32_e32 v97, v97
	v_rcp_f32_e32 v99, v99
	v_pk_mul_f32 v[82:83], v[82:83], v[140:141] op_sel_hi:[1,0]
	v_pk_mul_f32 v[80:81], v[80:81], v[140:141] op_sel_hi:[1,0]
	v_pk_mul_f32 v[82:83], v[86:87], v[82:83]
	v_pk_mul_f32 v[80:81], v[84:85], v[80:81]
	v_pk_mul_f32 v[84:85], v[82:83], v[92:93]
	v_pk_mul_f32 v[82:83], v[80:81], v[94:95]
	v_pk_mul_f32 v[90:91], v[90:91], v[96:97]
	v_pk_mul_f32 v[88:89], v[88:89], v[98:99]
	v_pk_mul_f32 v[78:79], v[78:79], v[136:137] op_sel_hi:[1,0]
	v_cvt_pk_bf16_f32 v80, v88, v89
	v_cvt_pk_bf16_f32 v81, v90, v91
	v_cvt_pk_bf16_f32 v82, v82, v83
	v_cvt_pk_bf16_f32 v83, v84, v85
	v_mad_i64_i32 v[84:85], s[4:5], v188, s35, v[112:113]
	v_lshl_add_u64 v[84:85], v[84:85], 0, v[114:115]
	v_pk_mul_f32 v[76:77], v[76:77], v[136:137] op_sel_hi:[1,0]
	v_pk_mul_f32 v[74:75], v[74:75], v[136:137] op_sel_hi:[1,0]
	v_pk_mul_f32 v[72:73], v[72:73], v[136:137] op_sel_hi:[1,0]
	v_pk_mul_f32 v[70:71], v[70:71], v[136:137] op_sel_hi:[1,0]
	v_pk_mul_f32 v[68:69], v[68:69], v[136:137] op_sel_hi:[1,0]
	global_store_dwordx4 v[84:85], v[80:83], off
	v_pk_mul_f32 v[72:73], v[76:77], v[72:73]
	v_pk_mul_f32 v[74:75], v[78:79], v[74:75]
	v_pk_mul_f32 v[80:81], v[78:79], s[44:45] op_sel_hi:[1,0]
	v_pk_mul_f32 v[82:83], v[76:77], s[44:45] op_sel_hi:[1,0]
	v_pk_mul_f32 v[76:77], v[70:71], s[44:45] op_sel_hi:[1,0]
	v_pk_mul_f32 v[78:79], v[68:69], s[44:45] op_sel_hi:[1,0]
	v_exp_f32_e32 v76, v76
	v_exp_f32_e32 v78, v78
	v_exp_f32_e32 v77, v77
	v_exp_f32_e32 v79, v79
	v_exp_f32_e32 v82, v82
	v_exp_f32_e32 v80, v80
	v_exp_f32_e32 v81, v81
	v_exp_f32_e32 v83, v83
	v_pk_add_f32 v[76:77], v[76:77], 1.0 op_sel_hi:[1,0]
	v_pk_add_f32 v[78:79], v[78:79], 1.0 op_sel_hi:[1,0]
	v_pk_add_f32 v[80:81], v[80:81], 1.0 op_sel_hi:[1,0]
	v_pk_add_f32 v[82:83], v[82:83], 1.0 op_sel_hi:[1,0]
	v_rcp_f32_e32 v78, v78
	v_rcp_f32_e32 v76, v76
	v_rcp_f32_e32 v77, v77
	v_rcp_f32_e32 v79, v79
	v_rcp_f32_e32 v82, v82
	v_rcp_f32_e32 v80, v80
	v_rcp_f32_e32 v81, v81
	v_rcp_f32_e32 v83, v83
	v_pk_mul_f32 v[66:67], v[66:67], v[136:137] op_sel_hi:[1,0]
	v_pk_mul_f32 v[64:65], v[64:65], v[136:137] op_sel_hi:[1,0]
	v_pk_mul_f32 v[66:67], v[70:71], v[66:67]
	v_pk_mul_f32 v[64:65], v[68:69], v[64:65]
	v_pk_mul_f32 v[68:69], v[66:67], v[76:77]
	v_pk_mul_f32 v[66:67], v[64:65], v[78:79]
	v_pk_mul_f32 v[74:75], v[74:75], v[80:81]
	v_pk_mul_f32 v[72:73], v[72:73], v[82:83]
	v_pk_mul_f32 v[62:63], v[62:63], v[134:135] op_sel_hi:[1,0]
	v_cvt_pk_bf16_f32 v64, v72, v73
	v_cvt_pk_bf16_f32 v65, v74, v75
	v_cvt_pk_bf16_f32 v66, v66, v67
	v_cvt_pk_bf16_f32 v67, v68, v69
	v_mad_i64_i32 v[68:69], s[4:5], v174, s35, v[112:113]
	v_lshl_add_u64 v[68:69], v[68:69], 0, v[114:115]
	v_pk_mul_f32 v[60:61], v[60:61], v[134:135] op_sel_hi:[1,0]
	v_pk_mul_f32 v[58:59], v[58:59], v[134:135] op_sel_hi:[1,0]
	v_pk_mul_f32 v[56:57], v[56:57], v[134:135] op_sel_hi:[1,0]
	v_pk_mul_f32 v[54:55], v[54:55], v[134:135] op_sel_hi:[1,0]
	v_pk_mul_f32 v[52:53], v[52:53], v[134:135] op_sel_hi:[1,0]
	global_store_dwordx4 v[68:69], v[64:67], off
	v_pk_mul_f32 v[56:57], v[60:61], v[56:57]
	v_pk_mul_f32 v[58:59], v[62:63], v[58:59]
	v_pk_mul_f32 v[64:65], v[62:63], s[44:45] op_sel_hi:[1,0]
	v_pk_mul_f32 v[66:67], v[60:61], s[44:45] op_sel_hi:[1,0]
	v_pk_mul_f32 v[60:61], v[54:55], s[44:45] op_sel_hi:[1,0]
	v_pk_mul_f32 v[62:63], v[52:53], s[44:45] op_sel_hi:[1,0]
	v_exp_f32_e32 v60, v60
	v_exp_f32_e32 v62, v62
	v_exp_f32_e32 v61, v61
	v_exp_f32_e32 v63, v63
	v_exp_f32_e32 v66, v66
	v_exp_f32_e32 v64, v64
	v_exp_f32_e32 v65, v65
	v_exp_f32_e32 v67, v67
	v_pk_add_f32 v[60:61], v[60:61], 1.0 op_sel_hi:[1,0]
	v_pk_add_f32 v[62:63], v[62:63], 1.0 op_sel_hi:[1,0]
	v_pk_add_f32 v[64:65], v[64:65], 1.0 op_sel_hi:[1,0]
	v_pk_add_f32 v[66:67], v[66:67], 1.0 op_sel_hi:[1,0]
	v_rcp_f32_e32 v62, v62
	v_rcp_f32_e32 v60, v60
	v_rcp_f32_e32 v61, v61
	v_rcp_f32_e32 v63, v63
	v_rcp_f32_e32 v66, v66
	v_rcp_f32_e32 v64, v64
	v_rcp_f32_e32 v65, v65
	v_rcp_f32_e32 v67, v67
	v_pk_mul_f32 v[50:51], v[50:51], v[134:135] op_sel_hi:[1,0]
	v_pk_mul_f32 v[48:49], v[48:49], v[134:135] op_sel_hi:[1,0]
	v_pk_mul_f32 v[50:51], v[54:55], v[50:51]
	v_pk_mul_f32 v[48:49], v[52:53], v[48:49]
	v_mul_f32_e32 v132, 0x45800000, v135
	v_pk_mul_f32 v[52:53], v[50:51], v[60:61]
	v_pk_mul_f32 v[50:51], v[48:49], v[62:63]
	v_cndmask_b32_e64 v132, v135, v132, s[6:7]
	v_pk_mul_f32 v[58:59], v[58:59], v[64:65]
	v_pk_mul_f32 v[56:57], v[56:57], v[66:67]
	v_pk_mul_f32 v[46:47], v[46:47], v[132:133] op_sel_hi:[1,0]
	v_cvt_pk_bf16_f32 v48, v56, v57
	v_cvt_pk_bf16_f32 v49, v58, v59
	v_cvt_pk_bf16_f32 v50, v50, v51
	v_cvt_pk_bf16_f32 v51, v52, v53
	v_mad_i64_i32 v[52:53], s[4:5], v172, s35, v[112:113]
	v_lshl_add_u64 v[52:53], v[52:53], 0, v[114:115]
	v_pk_mul_f32 v[44:45], v[44:45], v[132:133] op_sel_hi:[1,0]
	v_pk_mul_f32 v[42:43], v[42:43], v[132:133] op_sel_hi:[1,0]
	v_pk_mul_f32 v[40:41], v[40:41], v[132:133] op_sel_hi:[1,0]
	v_pk_mul_f32 v[38:39], v[38:39], v[132:133] op_sel_hi:[1,0]
	v_pk_mul_f32 v[36:37], v[36:37], v[132:133] op_sel_hi:[1,0]
	global_store_dwordx4 v[52:53], v[48:51], off
	v_pk_mul_f32 v[40:41], v[44:45], v[40:41]
	v_pk_mul_f32 v[42:43], v[46:47], v[42:43]
	v_pk_mul_f32 v[48:49], v[46:47], s[44:45] op_sel_hi:[1,0]
	v_pk_mul_f32 v[50:51], v[44:45], s[44:45] op_sel_hi:[1,0]
	v_pk_mul_f32 v[44:45], v[38:39], s[44:45] op_sel_hi:[1,0]
	v_pk_mul_f32 v[46:47], v[36:37], s[44:45] op_sel_hi:[1,0]
	v_exp_f32_e32 v44, v44
	v_exp_f32_e32 v46, v46
	v_exp_f32_e32 v45, v45
	v_exp_f32_e32 v47, v47
	v_exp_f32_e32 v50, v50
	v_exp_f32_e32 v48, v48
	v_exp_f32_e32 v49, v49
	v_exp_f32_e32 v51, v51
	v_pk_add_f32 v[44:45], v[44:45], 1.0 op_sel_hi:[1,0]
	v_pk_add_f32 v[46:47], v[46:47], 1.0 op_sel_hi:[1,0]
	v_pk_add_f32 v[48:49], v[48:49], 1.0 op_sel_hi:[1,0]
	v_pk_add_f32 v[50:51], v[50:51], 1.0 op_sel_hi:[1,0]
	v_rcp_f32_e32 v46, v46
	v_rcp_f32_e32 v44, v44
	v_rcp_f32_e32 v45, v45
	v_rcp_f32_e32 v47, v47
	v_rcp_f32_e32 v50, v50
	v_rcp_f32_e32 v48, v48
	v_rcp_f32_e32 v49, v49
	v_rcp_f32_e32 v51, v51
	v_pk_mul_f32 v[34:35], v[34:35], v[132:133] op_sel_hi:[1,0]
	v_pk_mul_f32 v[32:33], v[32:33], v[132:133] op_sel_hi:[1,0]
	v_pk_mul_f32 v[34:35], v[38:39], v[34:35]
	v_pk_mul_f32 v[32:33], v[36:37], v[32:33]
	v_pk_mul_f32 v[36:37], v[34:35], v[44:45]
	v_pk_mul_f32 v[34:35], v[32:33], v[46:47]
	v_pk_mul_f32 v[42:43], v[42:43], v[48:49]
	v_pk_mul_f32 v[40:41], v[40:41], v[50:51]
	v_pk_mul_f32 v[30:31], v[30:31], v[130:131] op_sel_hi:[1,0]
	v_cvt_pk_bf16_f32 v32, v40, v41
	v_cvt_pk_bf16_f32 v33, v42, v43
	v_cvt_pk_bf16_f32 v34, v34, v35
	v_cvt_pk_bf16_f32 v35, v36, v37
	v_mad_i64_i32 v[36:37], s[4:5], v170, s35, v[112:113]
	v_lshl_add_u64 v[36:37], v[36:37], 0, v[114:115]
	v_pk_mul_f32 v[28:29], v[28:29], v[130:131] op_sel_hi:[1,0]
	v_pk_mul_f32 v[26:27], v[26:27], v[130:131] op_sel_hi:[1,0]
	v_pk_mul_f32 v[24:25], v[24:25], v[130:131] op_sel_hi:[1,0]
	v_pk_mul_f32 v[22:23], v[22:23], v[130:131] op_sel_hi:[1,0]
	v_pk_mul_f32 v[20:21], v[20:21], v[130:131] op_sel_hi:[1,0]
	global_store_dwordx4 v[36:37], v[32:35], off
	v_pk_mul_f32 v[24:25], v[28:29], v[24:25]
	v_pk_mul_f32 v[26:27], v[30:31], v[26:27]
	v_pk_mul_f32 v[32:33], v[30:31], s[44:45] op_sel_hi:[1,0]
	v_pk_mul_f32 v[34:35], v[28:29], s[44:45] op_sel_hi:[1,0]
	v_pk_mul_f32 v[28:29], v[22:23], s[44:45] op_sel_hi:[1,0]
	v_pk_mul_f32 v[30:31], v[20:21], s[44:45] op_sel_hi:[1,0]
	v_exp_f32_e32 v28, v28
	v_exp_f32_e32 v30, v30
	v_exp_f32_e32 v29, v29
	v_exp_f32_e32 v31, v31
	v_exp_f32_e32 v34, v34
	v_exp_f32_e32 v32, v32
	v_exp_f32_e32 v33, v33
	v_exp_f32_e32 v35, v35
	v_pk_add_f32 v[28:29], v[28:29], 1.0 op_sel_hi:[1,0]
	v_pk_add_f32 v[30:31], v[30:31], 1.0 op_sel_hi:[1,0]
	v_pk_add_f32 v[32:33], v[32:33], 1.0 op_sel_hi:[1,0]
	v_pk_add_f32 v[34:35], v[34:35], 1.0 op_sel_hi:[1,0]
	v_rcp_f32_e32 v30, v30
	v_rcp_f32_e32 v28, v28
	v_rcp_f32_e32 v29, v29
	v_rcp_f32_e32 v31, v31
	v_rcp_f32_e32 v34, v34
	v_rcp_f32_e32 v32, v32
	v_rcp_f32_e32 v33, v33
	v_rcp_f32_e32 v35, v35
	v_pk_mul_f32 v[18:19], v[18:19], v[130:131] op_sel_hi:[1,0]
	v_pk_mul_f32 v[16:17], v[16:17], v[130:131] op_sel_hi:[1,0]
	v_pk_mul_f32 v[18:19], v[22:23], v[18:19]
	v_pk_mul_f32 v[16:17], v[20:21], v[16:17]
	v_pk_mul_f32 v[20:21], v[18:19], v[28:29]
	v_pk_mul_f32 v[18:19], v[16:17], v[30:31]
	v_pk_mul_f32 v[26:27], v[26:27], v[32:33]
	v_pk_mul_f32 v[24:25], v[24:25], v[34:35]
	v_pk_mul_f32 v[14:15], v[14:15], v[128:129] op_sel_hi:[1,0]
	v_cvt_pk_bf16_f32 v16, v24, v25
	v_cvt_pk_bf16_f32 v17, v26, v27
	v_cvt_pk_bf16_f32 v18, v18, v19
	v_cvt_pk_bf16_f32 v19, v20, v21
	v_mad_i64_i32 v[20:21], s[4:5], v168, s35, v[112:113]
	v_lshl_add_u64 v[20:21], v[20:21], 0, v[114:115]
	v_pk_mul_f32 v[12:13], v[12:13], v[128:129] op_sel_hi:[1,0]
	v_pk_mul_f32 v[10:11], v[10:11], v[128:129] op_sel_hi:[1,0]
	v_pk_mul_f32 v[8:9], v[8:9], v[128:129] op_sel_hi:[1,0]
	v_pk_mul_f32 v[6:7], v[6:7], v[128:129] op_sel_hi:[1,0]
	v_pk_mul_f32 v[4:5], v[4:5], v[128:129] op_sel_hi:[1,0]
	global_store_dwordx4 v[20:21], v[16:19], off
	v_pk_mul_f32 v[8:9], v[12:13], v[8:9]
	v_pk_mul_f32 v[10:11], v[14:15], v[10:11]
	v_pk_mul_f32 v[16:17], v[14:15], s[44:45] op_sel_hi:[1,0]
	v_pk_mul_f32 v[18:19], v[12:13], s[44:45] op_sel_hi:[1,0]
	v_pk_mul_f32 v[12:13], v[6:7], s[44:45] op_sel_hi:[1,0]
	v_pk_mul_f32 v[14:15], v[4:5], s[44:45] op_sel_hi:[1,0]
	v_exp_f32_e32 v12, v12
	v_exp_f32_e32 v14, v14
	v_exp_f32_e32 v13, v13
	v_exp_f32_e32 v15, v15
	v_exp_f32_e32 v18, v18
	v_exp_f32_e32 v16, v16
	v_exp_f32_e32 v17, v17
	v_exp_f32_e32 v19, v19
	v_pk_add_f32 v[12:13], v[12:13], 1.0 op_sel_hi:[1,0]
	v_pk_add_f32 v[14:15], v[14:15], 1.0 op_sel_hi:[1,0]
	v_pk_add_f32 v[16:17], v[16:17], 1.0 op_sel_hi:[1,0]
	v_pk_add_f32 v[18:19], v[18:19], 1.0 op_sel_hi:[1,0]
	v_rcp_f32_e32 v14, v14
	v_rcp_f32_e32 v12, v12
	v_rcp_f32_e32 v13, v13
	v_rcp_f32_e32 v15, v15
	v_rcp_f32_e32 v18, v18
	v_rcp_f32_e32 v16, v16
	v_rcp_f32_e32 v17, v17
	v_rcp_f32_e32 v19, v19
	v_pk_mul_f32 v[2:3], v[2:3], v[128:129] op_sel_hi:[1,0]
	v_pk_mul_f32 v[0:1], v[0:1], v[128:129] op_sel_hi:[1,0]
	v_pk_mul_f32 v[2:3], v[6:7], v[2:3]
	v_pk_mul_f32 v[0:1], v[4:5], v[0:1]
	v_pk_mul_f32 v[4:5], v[2:3], v[12:13]
	v_pk_mul_f32 v[2:3], v[0:1], v[14:15]
	v_pk_mul_f32 v[10:11], v[10:11], v[16:17]
	v_pk_mul_f32 v[8:9], v[8:9], v[18:19]
	s_andn2_b64 vcc, exec, s[2:3]
	v_cvt_pk_bf16_f32 v0, v8, v9
	v_cvt_pk_bf16_f32 v1, v10, v11
	v_cvt_pk_bf16_f32 v2, v2, v3
	v_cvt_pk_bf16_f32 v3, v4, v5
	v_mad_i64_i32 v[4:5], s[4:5], v166, s35, v[112:113]
	v_lshl_add_u64 v[4:5], v[4:5], 0, v[114:115]
	s_mov_b32 s4, s16
	s_mov_b32 s5, s12
	s_mov_b64 s[6:7], s[18:19]
	global_store_dwordx4 v[4:5], v[0:3], off
	s_cbranch_vccnz .LBB0_1429
	s_waitcnt vmcnt(0)
	s_cmpk_gt_u32 s24, 0xff
	s_cbranch_scc1 .LBB0_1440
	s_barrier

	.amdhsa_kernel _Z4mega6Params
		.amdhsa_group_segment_fixed_size 16384
		.amdhsa_private_segment_fixed_size 0
		.amdhsa_kernarg_size 512
		.amdhsa_user_sgpr_count 2
		.amdhsa_user_sgpr_dispatch_ptr 0
		.amdhsa_user_sgpr_queue_ptr 0
		.amdhsa_user_sgpr_kernarg_segment_ptr 1
		.amdhsa_user_sgpr_dispatch_id 0
		.amdhsa_user_sgpr_kernarg_preload_length 0
		.amdhsa_user_sgpr_kernarg_preload_offset 0
		.amdhsa_user_sgpr_private_segment_size 0
		.amdhsa_uses_dynamic_stack 0
		.amdhsa_enable_private_segment 0
		.amdhsa_system_sgpr_workgroup_id_x 1
		.amdhsa_system_sgpr_workgroup_id_y 0
		.amdhsa_system_sgpr_workgroup_id_z 0
		.amdhsa_system_sgpr_workgroup_info 0
		.amdhsa_system_vgpr_workitem_id 0
		.amdhsa_next_free_vgpr 255
		.amdhsa_next_free_sgpr 100
		.amdhsa_accum_offset 256
		.amdhsa_reserve_vcc 1
		.amdhsa_float_round_mode_32 0
		.amdhsa_float_round_mode_16_64 0
		.amdhsa_float_denorm_mode_32 3
		.amdhsa_float_denorm_mode_16_64 3
		.amdhsa_dx10_clamp 1
		.amdhsa_ieee_mode 1
		.amdhsa_fp16_overflow 0
		.amdhsa_tg_split 0
		.amdhsa_exception_fp_ieee_invalid_op 0
		.amdhsa_exception_fp_denorm_src 0
		.amdhsa_exception_fp_ieee_div_zero 0
		.amdhsa_exception_fp_ieee_overflow 0
		.amdhsa_exception_fp_ieee_underflow 0
		.amdhsa_exception_fp_ieee_inexact 0
		.amdhsa_exception_int_div_zero 0
	.end_amdhsa_kernel

amdhsa.kernels:
  - .agpr_count:     0
    .args:
      - .offset:         0
        .size:           256
        .value_kind:     by_value
      - .offset:         256
        .size:           4
        .value_kind:     hidden_block_count_x
      - .offset:         260
        .size:           4
        .value_kind:     hidden_block_count_y
      - .offset:         264
        .size:           4
        .value_kind:     hidden_block_count_z
      - .offset:         268
        .size:           2
        .value_kind:     hidden_group_size_x
      - .offset:         270
        .size:           2
        .value_kind:     hidden_group_size_y
      - .offset:         272
        .size:           2
        .value_kind:     hidden_group_size_z
      - .offset:         274
        .size:           2
        .value_kind:     hidden_remainder_x
      - .offset:         276
        .size:           2
        .value_kind:     hidden_remainder_y
      - .offset:         278
        .size:           2
        .value_kind:     hidden_remainder_z
      - .offset:         296
        .size:           8
        .value_kind:     hidden_global_offset_x
      - .offset:         304
        .size:           8
        .value_kind:     hidden_global_offset_y
      - .offset:         312
        .size:           8
        .value_kind:     hidden_global_offset_z
      - .offset:         320
        .size:           2
        .value_kind:     hidden_grid_dims
      - .offset:         376
        .size:           4
        .value_kind:     hidden_dynamic_lds_size
    .group_segment_fixed_size: 16384
    .kernarg_segment_align: 8
    .kernarg_segment_size: 512
    .language:       OpenCL C
    .language_version:
      - 2
      - 0
    .max_flat_workgroup_size: 512
    .name:           _Z4mega6Params
    .private_segment_fixed_size: 0
    .sgpr_count:     106
    .sgpr_spill_count: 6
    .symbol:         _Z4mega6Params.kd
    .uniform_work_group_size: 1
    .uses_dynamic_stack: false
    .vgpr_count:     255
    .vgpr_spill_count: 0
    .wavefront_size: 64
